# non-temporal loads in phase 0 and on the P7 residual row reads (mix / old residual are dead after the read)
# baseline (speedup 1.0000x reference)
.LBB0_945:
	v_mov_b32_e32 v1, v194
	v_mov_b32_e32 v7, v0
	v_ashrrev_i32_e32 v1, 6, v1
	v_add_u32_e32 v22, s2, v1
	v_mov_b32_e32 v1, v194
	v_ashrrev_i32_e32 v23, 31, v22
	v_and_b32_e32 v1, 63, v1
	s_waitcnt lgkmcnt(0)
	v_lshlrev_b64 v[2:3], 12, v[22:23]
	v_lshl_add_u64 v[4:5], s[98:99], 0, v[2:3]
	v_lshlrev_b32_e32 v6, 4, v1
	v_lshl_add_u64 v[4:5], v[4:5], 0, v[6:7]
	v_mov_b32_e32 v168, v4
	v_mov_b32_e32 v169, v5
	v_and_b32_e32 v4, 64, v203
	v_readlane_b32 s0, v230, 1
	v_xor_b32_e32 v5, 32, v203
	v_add_u32_e32 v100, 64, v4
	v_lshlrev_b32_e32 v54, 5, v1
	v_readlane_b32 s1, v230, 2
	v_cmp_lt_i32_e32 vcc, v5, v100
	v_lshl_add_u64 v[2:3], s[0:1], 0, v[2:3]
	v_cndmask_b32_e32 v4, v203, v5, vcc
	v_lshl_add_u64 v[24:25], v[2:3], 0, v[6:7]
	v_lshlrev_b32_e32 v58, 2, v4
	s_cmp_eq_u32 s78, 0
	s_cbranch_scc1 .Lp7_have
	global_load_dwordx4 v[104:107], v[168:169], off nt
	global_load_dwordx4 v[108:111], v[168:169], off offset:1024 nt
	global_load_dwordx4 v[112:115], v[168:169], off offset:2048 nt
	global_load_dwordx4 v[116:119], v[168:169], off offset:3072 nt
	global_load_dwordx4 v[120:123], v[24:25], off nt
	global_load_dwordx4 v[124:127], v[24:25], off offset:1024 nt
	global_load_dwordx4 v[128:131], v[24:25], off offset:2048 nt
	global_load_dwordx4 v[132:135], v[24:25], off offset:3072 nt
	s_mov_b32 s78, 0
	s_waitcnt vmcnt(0)
	s_branch .Lp7_mov

.Lp7_mov:
	v_mov_b32_e32 v14, v104
	v_mov_b32_e32 v15, v105
	v_mov_b32_e32 v16, v106
	v_mov_b32_e32 v17, v107
	v_mov_b32_e32 v18, v108
	v_mov_b32_e32 v19, v109
	v_mov_b32_e32 v20, v110
	v_mov_b32_e32 v21, v111
	v_mov_b32_e32 v26, v112
	v_mov_b32_e32 v27, v113
	v_mov_b32_e32 v28, v114
	v_mov_b32_e32 v29, v115
	v_mov_b32_e32 v42, v116
	v_mov_b32_e32 v43, v117
	v_mov_b32_e32 v44, v118
	v_mov_b32_e32 v45, v119
	v_mov_b32_e32 v72, v120
	v_mov_b32_e32 v73, v121
	v_mov_b32_e32 v74, v122
	v_mov_b32_e32 v75, v123
	v_mov_b32_e32 v10, v124
	v_mov_b32_e32 v11, v125
	v_mov_b32_e32 v12, v126
	v_mov_b32_e32 v13, v127
	v_mov_b32_e32 v6, v128
	v_mov_b32_e32 v7, v129
	v_mov_b32_e32 v8, v130
	v_mov_b32_e32 v9, v131
	v_mov_b32_e32 v2, v132
	v_mov_b32_e32 v3, v133
	v_mov_b32_e32 v4, v134
	v_mov_b32_e32 v5, v135
	s_add_i32 vcc_lo, s8, s34
	s_cmpk_gt_i32 vcc_lo, 0x7ff
	s_cbranch_scc1 .Lp7_nopf
	v_lshl_add_u64 v[168:169], v[168:169], 0, s[80:81]
	v_lshl_add_u64 v[170:171], v[24:25], 0, s[80:81]
	global_load_dwordx4 v[104:107], v[168:169], off nt
	global_load_dwordx4 v[108:111], v[168:169], off offset:1024 nt
	global_load_dwordx4 v[112:115], v[168:169], off offset:2048 nt
	global_load_dwordx4 v[116:119], v[168:169], off offset:3072 nt
	global_load_dwordx4 v[120:123], v[170:171], off nt
	global_load_dwordx4 v[124:127], v[170:171], off offset:1024 nt
	global_load_dwordx4 v[128:131], v[170:171], off offset:2048 nt
	global_load_dwordx4 v[132:135], v[170:171], off offset:3072 nt
